# speedup vs baseline: 1.0061x; 1.0005x over previous
; DEV uint32_t pack2(float a, float b) { const f32x2_t v = {a, b}; const bf16x2_t h = __builtin_convertvector(v, bf16x2_t); return __builtin_bit_cast(uint32_t, h); }
; DEV void ret_out_item(const Params& p, int l, int item, unsigned char* smem) {
;     ...
;   {
;     const float4* st = (const float4*)(p.prev + (size_t)sitem * 16384);
;     for (int c = tid; c < 128 * 32; c += NT) {
;       int e = c >> 5, d4 = (c & 31) * 4;
;       float4 v = st[c];
;       uint2 pk; pk.x = pack2(v.x, v.y); pk.y = pack2(v.z, v.w);
;       *(uint2*)(sST + e * KS + d4) = pk;
;     }
;   }
.LBB0_343:
	s_mov_b64 s[0:1], 0x2000
	global_load_dwordx4 v[200:203], v[40:41], off offset:-8
	v_lshl_add_u64 v[40:41], v[40:41], 0, s[0:1]
	global_load_dwordx4 v[204:207], v[40:41], off offset:-8
	v_lshl_add_u64 v[40:41], v[40:41], 0, s[0:1]
	global_load_dwordx4 v[208:211], v[40:41], off offset:-8
	v_lshl_add_u64 v[40:41], v[40:41], 0, s[0:1]
	global_load_dwordx4 v[212:215], v[40:41], off offset:-8
	v_lshl_add_u64 v[40:41], v[40:41], 0, s[0:1]
	global_load_dwordx4 v[216:219], v[40:41], off offset:-8
	v_lshl_add_u64 v[40:41], v[40:41], 0, s[0:1]
	global_load_dwordx4 v[220:223], v[40:41], off offset:-8
	v_lshl_add_u64 v[40:41], v[40:41], 0, s[0:1]
	global_load_dwordx4 v[224:227], v[40:41], off offset:-8
	v_lshl_add_u64 v[40:41], v[40:41], 0, s[0:1]
	global_load_dwordx4 v[228:231], v[40:41], off offset:-8
	v_ashrrev_i32_e32 v45, 5, v38
	v_and_b32_e32 v50, 0x7c, v39
	v_mul_lo_u32 v45, v45, s89
	v_lshlrev_b32_e32 v50, 1, v50
	v_add3_u32 v45, v45, v50, s18
	s_waitcnt vmcnt(7)
	v_cvt_pk_bf16_f32 v46, v200, v201
	v_cvt_pk_bf16_f32 v47, v202, v203
	ds_write_b64 v45, v[46:47]
	s_waitcnt vmcnt(6)
	v_cvt_pk_bf16_f32 v48, v204, v205
	v_cvt_pk_bf16_f32 v49, v206, v207
	ds_write_b64 v45, v[48:49] offset:4352
	s_waitcnt vmcnt(5)
	v_cvt_pk_bf16_f32 v46, v208, v209
	v_cvt_pk_bf16_f32 v47, v210, v211
	ds_write_b64 v45, v[46:47] offset:8704
	s_waitcnt vmcnt(4)
	v_cvt_pk_bf16_f32 v48, v212, v213
	v_cvt_pk_bf16_f32 v49, v214, v215
	ds_write_b64 v45, v[48:49] offset:13056
	s_waitcnt vmcnt(3)
	v_cvt_pk_bf16_f32 v46, v216, v217
	v_cvt_pk_bf16_f32 v47, v218, v219
	ds_write_b64 v45, v[46:47] offset:17408
	s_waitcnt vmcnt(2)
	v_cvt_pk_bf16_f32 v48, v220, v221
	v_cvt_pk_bf16_f32 v49, v222, v223
	ds_write_b64 v45, v[48:49] offset:21760
	s_waitcnt vmcnt(1)
	v_cvt_pk_bf16_f32 v46, v224, v225
	v_cvt_pk_bf16_f32 v47, v226, v227
	ds_write_b64 v45, v[46:47] offset:26112
	s_waitcnt vmcnt(0)
	v_cvt_pk_bf16_f32 v48, v228, v229
	v_cvt_pk_bf16_f32 v49, v230, v231
	ds_write_b64 v45, v[48:49] offset:30464
